# retstate: state-tile stores widened to 2 x dwordx4 per lane via permlane32_swap half exchange (was 4 x dwordx2)
# speedup vs baseline: 1.0158x; 1.0076x over previous
.LBB0_711:
	s_add_i32 s23, s12, -2
	s_add_i32 s24, s13, 2
	s_and_b64 s[16:17], s[6:7], exec
	s_cselect_b32 s16, s23, s24
	s_add_u32 s16, s10, s16
	s_addc_u32 s17, s11, 0
	s_lshl_b64 s[16:17], s[16:17], 15
	v_lshl_add_u64 v[66:67], v[114:115], 0, s[16:17]
	v_cvt_pk_bf16_f32 v68, v0, v1
	v_cvt_pk_bf16_f32 v69, v2, v3
	v_cvt_pk_bf16_f32 v70, v4, v5
	v_cvt_pk_bf16_f32 v71, v6, v7
	v_cvt_pk_bf16_f32 v72, v8, v9
	v_cvt_pk_bf16_f32 v73, v10, v11
	v_cvt_pk_bf16_f32 v74, v12, v13
	v_cvt_pk_bf16_f32 v75, v14, v15
	v_and_b32_e32 v76, 32, v210
	v_lshrrev_b32_e32 v76, 2, v76
	v_mov_b32_e32 v77, 0
	v_lshl_add_u64 v[66:67], v[66:67], 0, v[76:77]
	v_permlane32_swap_b32 v68, v70
	v_permlane32_swap_b32 v69, v71
	v_permlane32_swap_b32 v72, v74
	v_permlane32_swap_b32 v73, v75
	global_store_dwordx4 v[66:67], v[68:71], off
	global_store_dwordx4 v[66:67], v[72:75], off offset:32
	v_pk_mul_f32 v[14:15], v[112:113], v[14:15]
	v_pk_mul_f32 v[12:13], v[112:113], v[12:13]
	v_pk_mul_f32 v[10:11], v[112:113], v[10:11]
	v_pk_mul_f32 v[8:9], v[112:113], v[8:9]
	v_pk_mul_f32 v[6:7], v[112:113], v[6:7]
	v_pk_mul_f32 v[4:5], v[112:113], v[4:5]
	v_pk_mul_f32 v[2:3], v[112:113], v[2:3]
	v_pk_mul_f32 v[0:1], v[116:117], v[0:1]
	ds_read_b64_tr_b16 v[78:79], v121 offset:0
	ds_read_b64_tr_b16 v[80:81], v121 offset:1088
	ds_read_b64_tr_b16 v[74:75], v121 offset:4352
	ds_read_b64_tr_b16 v[76:77], v121 offset:5440
	ds_read_b64_tr_b16 v[70:71], v121 offset:8704
	ds_read_b64_tr_b16 v[72:73], v121 offset:9792
	ds_read_b64_tr_b16 v[66:67], v121 offset:13056
	ds_read_b64_tr_b16 v[68:69], v121 offset:14144
	s_waitcnt lgkmcnt(0)
	ds_read_b64_tr_b16 v[94:95], v122 offset:0
	ds_read_b64_tr_b16 v[96:97], v122 offset:1088
	ds_read_b64_tr_b16 v[90:91], v122 offset:4352
	ds_read_b64_tr_b16 v[92:93], v122 offset:5440
	ds_read_b64_tr_b16 v[86:87], v122 offset:8704
	ds_read_b64_tr_b16 v[88:89], v122 offset:9792
	ds_read_b64_tr_b16 v[82:83], v122 offset:13056
	ds_read_b64_tr_b16 v[84:85], v122 offset:14144
	s_waitcnt lgkmcnt(0)
	s_add_i32 s12, s12, 2
	s_add_i32 s13, s13, -2
	v_mfma_f32_32x32x16_bf16 v[0:15], v[78:81], v[94:97], v[0:15]
	s_cmp_gt_u32 s15, 13
	v_mfma_f32_32x32x16_bf16 v[0:15], v[74:77], v[90:93], v[0:15]
	v_mfma_f32_32x32x16_bf16 v[0:15], v[70:73], v[86:89], v[0:15]
	v_mfma_f32_32x32x16_bf16 v[0:15], v[66:69], v[82:85], v[0:15]
	ds_read_b64_tr_b16 v[78:79], v136 offset:0
	ds_read_b64_tr_b16 v[80:81], v136 offset:1088
	ds_read_b64_tr_b16 v[74:75], v136 offset:4352
	ds_read_b64_tr_b16 v[76:77], v136 offset:5440
	ds_read_b64_tr_b16 v[70:71], v136 offset:8704
	ds_read_b64_tr_b16 v[72:73], v136 offset:9792
	ds_read_b64_tr_b16 v[66:67], v136 offset:13056
	ds_read_b64_tr_b16 v[68:69], v136 offset:14144
	s_waitcnt lgkmcnt(0)
	ds_read_b64_tr_b16 v[94:95], v137 offset:0
	ds_read_b64_tr_b16 v[96:97], v137 offset:1088
	ds_read_b64_tr_b16 v[90:91], v137 offset:4352
	ds_read_b64_tr_b16 v[92:93], v137 offset:5440
	ds_read_b64_tr_b16 v[86:87], v137 offset:8704
	ds_read_b64_tr_b16 v[88:89], v137 offset:9792
	ds_read_b64_tr_b16 v[82:83], v137 offset:13056
	ds_read_b64_tr_b16 v[84:85], v137 offset:14144
	s_waitcnt lgkmcnt(0)
	s_nop 0
	v_mfma_f32_32x32x16_bf16 v[0:15], v[78:81], v[94:97], v[0:15]
	v_mfma_f32_32x32x16_bf16 v[0:15], v[74:77], v[90:93], v[0:15]
	v_mfma_f32_32x32x16_bf16 v[0:15], v[70:73], v[86:89], v[0:15]
	v_mfma_f32_32x32x16_bf16 v[0:15], v[66:69], v[82:85], v[0:15]
	s_cbranch_scc1 .LBB0_709

.LBB0_714:
	s_add_i32 s23, s13, 3
	s_and_b64 s[16:17], s[6:7], exec
	s_cselect_b32 s16, s15, s23
	s_add_u32 s16, s10, s16
	s_addc_u32 s17, s11, 0
	s_lshl_b64 s[16:17], s[16:17], 15
	v_lshl_add_u64 v[66:67], v[114:115], 0, s[16:17]
	v_cvt_pk_bf16_f32 v68, v0, v1
	v_cvt_pk_bf16_f32 v69, v2, v3
	v_cvt_pk_bf16_f32 v70, v4, v5
	v_cvt_pk_bf16_f32 v71, v6, v7
	v_cvt_pk_bf16_f32 v72, v8, v9
	v_cvt_pk_bf16_f32 v73, v10, v11
	v_cvt_pk_bf16_f32 v74, v12, v13
	v_cvt_pk_bf16_f32 v75, v14, v15
	v_and_b32_e32 v76, 32, v210
	v_lshrrev_b32_e32 v76, 2, v76
	v_mov_b32_e32 v77, 0
	v_lshl_add_u64 v[66:67], v[66:67], 0, v[76:77]
	v_permlane32_swap_b32 v68, v70
	v_permlane32_swap_b32 v69, v71
	v_permlane32_swap_b32 v72, v74
	v_permlane32_swap_b32 v73, v75
	global_store_dwordx4 v[66:67], v[68:71], off
	global_store_dwordx4 v[66:67], v[72:75], off offset:32
	v_mov_b32_e32 v113, v112
	v_pk_mul_f32 v[14:15], v[112:113], v[14:15]
	v_pk_mul_f32 v[12:13], v[112:113], v[12:13]
	v_pk_mul_f32 v[10:11], v[112:113], v[10:11]
	v_pk_mul_f32 v[8:9], v[112:113], v[8:9]
	v_pk_mul_f32 v[6:7], v[112:113], v[6:7]
	v_pk_mul_f32 v[4:5], v[112:113], v[4:5]
	v_pk_mul_f32 v[2:3], v[112:113], v[2:3]
	v_pk_mul_f32 v[0:1], v[116:117], v[0:1]
	ds_read_b64_tr_b16 v[78:79], v119 offset:0
	ds_read_b64_tr_b16 v[80:81], v119 offset:1088
	ds_read_b64_tr_b16 v[74:75], v119 offset:4352
	ds_read_b64_tr_b16 v[76:77], v119 offset:5440
	ds_read_b64_tr_b16 v[70:71], v119 offset:8704
	ds_read_b64_tr_b16 v[72:73], v119 offset:9792
	ds_read_b64_tr_b16 v[66:67], v119 offset:13056
	ds_read_b64_tr_b16 v[68:69], v119 offset:14144
	s_waitcnt lgkmcnt(0)
	ds_read_b64_tr_b16 v[94:95], v120 offset:0
	ds_read_b64_tr_b16 v[96:97], v120 offset:1088
	ds_read_b64_tr_b16 v[90:91], v120 offset:4352
	ds_read_b64_tr_b16 v[92:93], v120 offset:5440
	ds_read_b64_tr_b16 v[86:87], v120 offset:8704
	ds_read_b64_tr_b16 v[88:89], v120 offset:9792
	ds_read_b64_tr_b16 v[82:83], v120 offset:13056
	ds_read_b64_tr_b16 v[84:85], v120 offset:14144
	s_waitcnt lgkmcnt(0)
	s_waitcnt vmcnt(7)
	v_lshlrev_b32_e32 v105, 16, v34
	v_and_b32_e32 v107, 0xffff0000, v34
	v_mfma_f32_32x32x16_bf16 v[0:15], v[78:81], v[94:97], v[0:15]
	v_lshlrev_b32_e32 v142, 16, v35
	v_and_b32_e32 v143, 0xffff0000, v35
	v_lshlrev_b32_e32 v144, 16, v36
	v_and_b32_e32 v145, 0xffff0000, v36
	v_mul_f32_e32 v105, v103, v105
	v_lshlrev_b32_e32 v146, 16, v37
	v_and_b32_e32 v147, 0xffff0000, v37
	v_mfma_f32_32x32x16_bf16 v[0:15], v[74:77], v[90:93], v[0:15]
	v_mul_f32_e32 v107, v103, v107
	v_mul_f32_e32 v148, v103, v142
	v_mul_f32_e32 v143, v103, v143
	v_mul_f32_e32 v144, v103, v144
	v_mul_f32_e32 v145, v103, v145
	v_cvt_pk_bf16_f32 v142, v105, v107
	v_add_u32_e32 v105, s92, v130
	v_mfma_f32_32x32x16_bf16 v[0:15], v[70:73], v[86:89], v[0:15]
	v_mul_f32_e32 v146, v103, v146
	v_mul_f32_e32 v147, v103, v147
	v_cvt_pk_bf16_f32 v143, v148, v143
	v_cvt_pk_bf16_f32 v144, v144, v145
	v_cvt_pk_bf16_f32 v145, v146, v147
	s_waitcnt vmcnt(6)
	v_and_b32_e32 v107, 0xffff0000, v38
	v_lshlrev_b32_e32 v146, 16, v41
	v_mfma_f32_32x32x16_bf16 v[0:15], v[66:69], v[82:85], v[0:15]
	ds_read_b64_tr_b16 v[90:91], v134 offset:0
	ds_read_b64_tr_b16 v[92:93], v134 offset:1088
	ds_read_b64_tr_b16 v[82:83], v134 offset:4352
	ds_read_b64_tr_b16 v[84:85], v134 offset:5440
	ds_read_b64_tr_b16 v[74:75], v134 offset:8704
	ds_read_b64_tr_b16 v[76:77], v134 offset:9792
	ds_read_b64_tr_b16 v[66:67], v134 offset:13056
	ds_read_b64_tr_b16 v[68:69], v134 offset:14144
	s_waitcnt lgkmcnt(0)
	ds_read_b64_tr_b16 v[94:95], v135 offset:0
	ds_read_b64_tr_b16 v[96:97], v135 offset:1088
	ds_read_b64_tr_b16 v[86:87], v135 offset:4352
	ds_read_b64_tr_b16 v[88:89], v135 offset:5440
	ds_read_b64_tr_b16 v[78:79], v135 offset:8704
	ds_read_b64_tr_b16 v[80:81], v135 offset:9792
	ds_read_b64_tr_b16 v[70:71], v135 offset:13056
	ds_read_b64_tr_b16 v[72:73], v135 offset:14144
	s_waitcnt lgkmcnt(0)
	ds_write_b128 v105, v[142:145]
	v_lshlrev_b32_e32 v105, 16, v38
	v_lshlrev_b32_e32 v142, 16, v39
	v_and_b32_e32 v143, 0xffff0000, v39
	v_lshlrev_b32_e32 v144, 16, v40
	v_mfma_f32_32x32x16_bf16 v[0:15], v[90:93], v[94:97], v[0:15]
	v_and_b32_e32 v145, 0xffff0000, v40
	v_mul_f32_e32 v105, v139, v105
	v_and_b32_e32 v147, 0xffff0000, v41
	v_mul_f32_e32 v107, v139, v107
	v_mul_f32_e32 v148, v139, v142
	v_mul_f32_e32 v143, v139, v143
	v_mul_f32_e32 v144, v139, v144
	v_mfma_f32_32x32x16_bf16 v[0:15], v[82:85], v[86:89], v[0:15]
	v_mul_f32_e32 v145, v139, v145
	v_cvt_pk_bf16_f32 v142, v105, v107
	v_add_u32_e32 v105, s92, v131
	v_mul_f32_e32 v146, v139, v146
	v_mul_f32_e32 v147, v139, v147
	v_cvt_pk_bf16_f32 v143, v148, v143
	v_cvt_pk_bf16_f32 v144, v144, v145
	v_mfma_f32_32x32x16_bf16 v[0:15], v[74:77], v[78:81], v[0:15]
	v_cvt_pk_bf16_f32 v145, v146, v147
	ds_write_b128 v105, v[142:145]
	s_waitcnt vmcnt(5)
	v_lshlrev_b32_e32 v105, 16, v50
	v_and_b32_e32 v107, 0xffff0000, v50
	v_lshlrev_b32_e32 v142, 16, v51
	v_and_b32_e32 v143, 0xffff0000, v51
	v_lshlrev_b32_e32 v144, 16, v52
	v_mfma_f32_32x32x16_bf16 v[0:15], v[66:69], v[70:73], v[0:15]
	v_and_b32_e32 v145, 0xffff0000, v52
	v_mul_f32_e32 v105, v140, v105
	v_lshlrev_b32_e32 v146, 16, v53
	v_and_b32_e32 v147, 0xffff0000, v53
	v_mul_f32_e32 v107, v140, v107
	v_mul_f32_e32 v148, v140, v142
	v_mul_f32_e32 v143, v140, v143
	v_mul_f32_e32 v144, v140, v144
	v_mul_f32_e32 v145, v140, v145
	v_cvt_pk_bf16_f32 v142, v105, v107
	v_add_u32_e32 v105, s92, v132
	v_mul_f32_e32 v146, v140, v146
	v_mul_f32_e32 v147, v140, v147
	v_cvt_pk_bf16_f32 v143, v148, v143
	v_cvt_pk_bf16_f32 v144, v144, v145
	v_cvt_pk_bf16_f32 v145, v146, v147
	ds_write_b128 v105, v[142:145]
	s_waitcnt vmcnt(4)
	v_lshlrev_b32_e32 v105, 16, v54
	v_and_b32_e32 v107, 0xffff0000, v54
	v_lshlrev_b32_e32 v142, 16, v55
	v_and_b32_e32 v143, 0xffff0000, v55
	v_lshlrev_b32_e32 v144, 16, v56
	v_and_b32_e32 v145, 0xffff0000, v56
	v_mul_f32_e32 v105, v141, v105
	v_lshlrev_b32_e32 v146, 16, v57
	v_and_b32_e32 v147, 0xffff0000, v57
	v_mul_f32_e32 v107, v141, v107
	v_mul_f32_e32 v148, v141, v142
	v_mul_f32_e32 v143, v141, v143
	v_mul_f32_e32 v144, v141, v144
	v_mul_f32_e32 v145, v141, v145
	v_cvt_pk_bf16_f32 v142, v105, v107
	v_add_u32_e32 v105, s92, v133
	v_mul_f32_e32 v146, v141, v146
	v_mul_f32_e32 v147, v141, v147
	v_cvt_pk_bf16_f32 v143, v148, v143
	v_cvt_pk_bf16_f32 v144, v144, v145
	v_cvt_pk_bf16_f32 v145, v146, v147
	ds_write_b128 v105, v[142:145]
	v_add_u32_e32 v105, 0x19800, v138
	s_cmp_gt_u32 s15, 12
	s_waitcnt vmcnt(3)
	ds_write_b128 v105, v[58:61]
	s_waitcnt vmcnt(2)
	ds_write_b128 v105, v[62:65] offset:17408
	s_waitcnt lgkmcnt(0)
	s_barrier
	s_cbranch_scc1 .LBB0_711
	s_and_b64 s[16:17], s[6:7], exec
	s_cselect_b32 s16, s12, s13
	s_mul_i32 s88, s16, 0x160000
	v_lshl_add_u64 v[50:51], v[108:109], 0, s[88:89]
	v_add_co_u32_e32 v38, vcc, 0x58000, v50
	v_lshl_add_u64 v[58:59], v[110:111], 0, s[88:89]
	s_nop 0
	v_addc_co_u32_e32 v39, vcc, 0, v51, vcc
	v_add_co_u32_e32 v52, vcc, 0xb0000, v50
	global_load_dwordx4 v[34:37], v[50:51], off
	s_nop 0
	global_load_dwordx4 v[38:41], v[38:39], off
	v_addc_co_u32_e32 v53, vcc, 0, v51, vcc
	v_add_co_u32_e32 v54, vcc, 0x108000, v50
	s_nop 1
	v_addc_co_u32_e32 v55, vcc, 0, v51, vcc
	v_add_co_u32_e32 v62, vcc, 0xb0000, v58
	global_load_dwordx4 v[50:53], v[52:53], off
	s_nop 0
	global_load_dwordx4 v[54:57], v[54:55], off
	v_addc_co_u32_e32 v63, vcc, 0, v59, vcc
	global_load_dwordx4 v[58:61], v[58:59], off
	s_nop 0
	global_load_dwordx4 v[62:65], v[62:63], off
	s_branch .LBB0_711
